# grid barriers: single-hop release by the last arriver, static generation, cache invalidate issued at arrival (overlaps the wait)
# speedup vs baseline: 1.0340x; 1.0114x over previous
.LBB0_115:
	s_waitcnt lgkmcnt(0)
	v_readfirstlane_b32 s1, v2
	v_readfirstlane_b32 s12, v0
	s_lshl_b32 s0, s0, 8
	s_add_u32 s8, s6, s0
	s_addc_u32 s9, s7, 0
	v_mov_b32_e32 v3, 0x1000
	v_mov_b32_e32 v4, 1
	v_mov_b32_e32 v0, 0x2000
	global_atomic_add v3, v3, v4, s[8:9] offset:1024 sc0
	s_mul_i32 s1, s1, 1
	s_mul_i32 s12, s12, 1
	s_mov_b32 s15, 0
	s_waitcnt vmcnt(0)
	v_readfirstlane_b32 s13, v3
	s_add_u32 s13, s13, 1
	s_cmp_lg_u32 s13, s1
	s_cbranch_scc1 .Lxb0_wait
	buffer_wbl2 sc1
	buffer_inv sc1
	s_waitcnt vmcnt(0)
	v_mov_b32_e32 v3, 0x3000
	global_atomic_add v3, v3, v4, s[6:7] offset:1024 sc0
	s_waitcnt vmcnt(0)
	v_readfirstlane_b32 s13, v3
	s_add_u32 s13, s13, 1
	s_cmp_lg_u32 s13, s12
	s_cbranch_scc1 .Lxb0_poll
	v_mov_b32_e32 v5, 0x3000
	global_atomic_add v0, v4, s[6:7] offset:1024
	global_atomic_add v0, v4, s[6:7] offset:1280
	global_atomic_add v0, v4, s[6:7] offset:1536
	global_atomic_add v0, v4, s[6:7] offset:1792
	global_atomic_add v0, v4, s[6:7] offset:2048
	global_atomic_add v0, v4, s[6:7] offset:2304
	global_atomic_add v0, v4, s[6:7] offset:2560
	global_atomic_add v0, v4, s[6:7] offset:2816
	global_atomic_add v0, v4, s[6:7] offset:3072
	global_atomic_add v0, v4, s[6:7] offset:3328
	global_atomic_add v0, v4, s[6:7] offset:3584
	global_atomic_add v0, v4, s[6:7] offset:3840
	global_atomic_add v5, v4, s[6:7]
	global_atomic_add v5, v4, s[6:7] offset:256
	global_atomic_add v5, v4, s[6:7] offset:512
	global_atomic_add v5, v4, s[6:7] offset:768
	s_waitcnt vmcnt(0)
	s_branch .Lxb0_done

.Lxb0_poll:
	global_load_dword v1, v0, s[8:9] offset:1024 sc1
	s_add_u32 s15, s15, 1
	s_waitcnt vmcnt(0)
	v_readfirstlane_b32 s14, v1
	s_cmp_lg_u32 s14, 0
	s_cbranch_scc1 .Lxb0_rel
	s_cmp_lt_u32 s15, 0x40000
	s_cbranch_scc0 .Lxb0_rel
	s_sleep 1
	s_branch .Lxb0_poll
.Lxb0_rel:
.Lxb0_done:
.LBB0_151:
	s_or_b64 exec, exec, s[4:5]
	s_mov_b32 s0, 0
	s_waitcnt lgkmcnt(0)
	s_barrier
	s_load_dwordx2 s[18:19], s[82:83], 0xb0
	v_mbcnt_lo_u32_b32 v0, -1, s0
	s_waitcnt vmcnt(10)
	v_mbcnt_hi_u32_b32 v8, -1, v0
	s_waitcnt lgkmcnt(0)
	s_add_u32 s4, s18, 0x10000
	s_addc_u32 s5, s19, 0
	s_add_i32 s0, s72, s3
	v_add_u32_e32 v0, s0, v8
	s_movk_i32 s0, 0x3c00
	v_cmp_gt_i32_e32 vcc, s0, v0
	s_and_saveexec_b64 s[6:7], vcc
	s_cbranch_execz .LBB0_161
	v_ashrrev_i32_e32 v1, 10, v0
	s_mov_b32 s0, 0x66666667
	v_mul_hi_i32 v2, v1, s0
	v_lshrrev_b32_e32 v3, 31, v2
	v_ashrrev_i32_e32 v2, 1, v2
	v_add_u32_e32 v2, v2, v3
	v_lshl_add_u32 v2, v2, 2, v2
	v_sub_u32_e32 v1, v1, v2
	v_add_u32_e32 v2, 0x13ff, v0
	s_movk_i32 s1, 0x27fe
	v_and_b32_e32 v6, 0x3ff, v0
	s_movk_i32 s0, 0x13ff
	v_cmp_lt_u32_e32 vcc, s1, v2
	s_and_saveexec_b64 s[2:3], vcc
	s_xor_b64 s[8:9], exec, s[2:3]
	s_cbranch_execz .LBB0_158
	v_add_u32_e32 v2, 0xffffec00, v0
	v_cmp_lt_u32_e32 vcc, s0, v2
	v_mov_b32_e32 v7, 0
	s_and_saveexec_b64 s[0:1], vcc
	s_xor_b64 s[12:13], exec, s[0:1]
	s_cbranch_execz .LBB0_155
	s_load_dwordx2 s[0:1], s[82:83], 0x38
	v_lshlrev_b32_e32 v6, 2, v6
	v_add_u32_e32 v1, 5, v1
	v_mov_b64_e32 v[4:5], s[4:5]
	s_mov_b64 s[2:3], 0x1000
	s_waitcnt lgkmcnt(0)
	v_lshl_add_u64 v[2:3], s[0:1], 0, v[6:7]
	s_movk_i32 s0, 0x6000
	v_mad_u64_u32 v[4:5], s[0:1], v1, s0, v[4:5]
	v_lshl_add_u64 v[4:5], v[4:5], 0, v[6:7]
	s_mov_b64 s[0:1], 0x4000
	v_lshl_add_u64 v[2:3], v[2:3], 0, s[2:3]
	v_lshl_add_u64 v[4:5], v[4:5], 0, s[0:1]

.LBB0_184:
	s_waitcnt lgkmcnt(0)
	v_readfirstlane_b32 s1, v2
	v_readfirstlane_b32 s8, v0
	s_lshl_b32 s0, s0, 8
	s_add_u32 s2, s6, s0
	s_addc_u32 s3, s7, 0
	v_mov_b32_e32 v3, 0x1000
	v_mov_b32_e32 v4, 1
	v_mov_b32_e32 v0, 0x2000
	global_atomic_add v3, v3, v4, s[2:3] offset:1024 sc0
	s_mul_i32 s1, s1, 2
	s_mul_i32 s8, s8, 2
	s_mov_b32 s13, 0
	s_waitcnt vmcnt(0)
	v_readfirstlane_b32 s9, v3
	s_add_u32 s9, s9, 1
	s_cmp_lg_u32 s9, s1
	s_cbranch_scc1 .Lxb1_wait
	buffer_wbl2 sc1
	buffer_inv sc1
	s_waitcnt vmcnt(0)
	v_mov_b32_e32 v3, 0x3000
	global_atomic_add v3, v3, v4, s[6:7] offset:1024 sc0
	s_waitcnt vmcnt(0)
	v_readfirstlane_b32 s9, v3
	s_add_u32 s9, s9, 1
	s_cmp_lg_u32 s9, s8
	s_cbranch_scc1 .Lxb1_poll
	v_mov_b32_e32 v5, 0x3000
	global_atomic_add v0, v4, s[6:7] offset:1024
	global_atomic_add v0, v4, s[6:7] offset:1280
	global_atomic_add v0, v4, s[6:7] offset:1536
	global_atomic_add v0, v4, s[6:7] offset:1792
	global_atomic_add v0, v4, s[6:7] offset:2048
	global_atomic_add v0, v4, s[6:7] offset:2304
	global_atomic_add v0, v4, s[6:7] offset:2560
	global_atomic_add v0, v4, s[6:7] offset:2816
	global_atomic_add v0, v4, s[6:7] offset:3072
	global_atomic_add v0, v4, s[6:7] offset:3328
	global_atomic_add v0, v4, s[6:7] offset:3584
	global_atomic_add v0, v4, s[6:7] offset:3840
	global_atomic_add v5, v4, s[6:7]
	global_atomic_add v5, v4, s[6:7] offset:256
	global_atomic_add v5, v4, s[6:7] offset:512
	global_atomic_add v5, v4, s[6:7] offset:768
	s_waitcnt vmcnt(0)
	s_branch .Lxb1_done

.Lxb1_poll:
	global_load_dword v1, v0, s[2:3] offset:1024 sc1
	s_add_u32 s13, s13, 1
	s_waitcnt vmcnt(0)
	v_readfirstlane_b32 s12, v1
	s_cmp_lg_u32 s12, 1
	s_cbranch_scc1 .Lxb1_rel
	s_cmp_lt_u32 s13, 0x40000
	s_cbranch_scc0 .Lxb1_rel
	s_sleep 1
	s_branch .Lxb1_poll
.Lxb1_rel:
.Lxb1_done:
.LBB0_220:
	s_or_b64 exec, exec, s[4:5]
	s_waitcnt lgkmcnt(0)
	s_barrier
	s_load_dwordx2 s[8:9], s[82:83], 0xb0
	s_lshl_b32 s0, s64, 5
	s_lshr_b32 s63, s68, 8
	s_and_b32 s55, s0, 0x60
	s_mov_b32 s54, 0
	s_mov_b32 s1, 0
	s_cmpk_lt_i32 s93, 0x154
	s_cbranch_scc1 .LBB0_222
	s_ashr_i32 s57, s74, 31
	s_mov_b32 s56, s74
	s_mov_b64 s[4:5], 0
	s_branch .LBB0_223

.LBB0_402:
	s_waitcnt lgkmcnt(0)
	v_readfirstlane_b32 s1, v2
	v_readfirstlane_b32 s12, v0
	s_lshl_b32 s0, s0, 8
	s_add_u32 s8, s6, s0
	s_addc_u32 s9, s7, 0
	v_mov_b32_e32 v3, 0x1000
	v_mov_b32_e32 v4, 1
	v_mov_b32_e32 v0, 0x2000
	global_atomic_add v3, v3, v4, s[8:9] offset:1024 sc0
	s_mul_i32 s1, s1, 3
	s_mul_i32 s12, s12, 3
	s_mov_b32 s15, 0
	s_waitcnt vmcnt(0)
	v_readfirstlane_b32 s13, v3
	s_add_u32 s13, s13, 1
	s_cmp_lg_u32 s13, s1
	s_cbranch_scc1 .Lxb2_wait
	buffer_wbl2 sc1
	buffer_inv sc1
	s_waitcnt vmcnt(0)
	v_mov_b32_e32 v3, 0x3000
	global_atomic_add v3, v3, v4, s[6:7] offset:1024 sc0
	s_waitcnt vmcnt(0)
	v_readfirstlane_b32 s13, v3
	s_add_u32 s13, s13, 1
	s_cmp_lg_u32 s13, s12
	s_cbranch_scc1 .Lxb2_poll
	v_mov_b32_e32 v5, 0x3000
	global_atomic_add v0, v4, s[6:7] offset:1024
	global_atomic_add v0, v4, s[6:7] offset:1280
	global_atomic_add v0, v4, s[6:7] offset:1536
	global_atomic_add v0, v4, s[6:7] offset:1792
	global_atomic_add v0, v4, s[6:7] offset:2048
	global_atomic_add v0, v4, s[6:7] offset:2304
	global_atomic_add v0, v4, s[6:7] offset:2560
	global_atomic_add v0, v4, s[6:7] offset:2816
	global_atomic_add v0, v4, s[6:7] offset:3072
	global_atomic_add v0, v4, s[6:7] offset:3328
	global_atomic_add v0, v4, s[6:7] offset:3584
	global_atomic_add v0, v4, s[6:7] offset:3840
	global_atomic_add v5, v4, s[6:7]
	global_atomic_add v5, v4, s[6:7] offset:256
	global_atomic_add v5, v4, s[6:7] offset:512
	global_atomic_add v5, v4, s[6:7] offset:768
	s_waitcnt vmcnt(0)
	s_branch .Lxb2_done

.Lxb2_poll:
	global_load_dword v1, v0, s[8:9] offset:1024 sc1
	s_add_u32 s15, s15, 1
	s_waitcnt vmcnt(0)
	v_readfirstlane_b32 s14, v1
	s_cmp_lg_u32 s14, 2
	s_cbranch_scc1 .Lxb2_rel
	s_cmp_lt_u32 s15, 0x40000
	s_cbranch_scc0 .Lxb2_rel
	s_sleep 1
	s_branch .Lxb2_poll
.Lxb2_rel:
.Lxb2_done:
.LBB0_438:
	s_or_b64 exec, exec, s[4:5]
	s_mov_b32 s1, 0
	s_waitcnt lgkmcnt(0)
	s_barrier
	s_load_dwordx2 s[6:7], s[82:83], 0xb0
	s_cmpk_lt_i32 s93, 0x100
	s_cselect_b64 s[4:5], -1, 0
	s_cmpk_gt_i32 s93, 0xff
	s_cselect_b64 s[8:9], -1, 0
	s_mov_b32 s0, 0
	v_writelane_b32 v254, s8, 2
	s_and_b64 vcc, exec, s[8:9]
	s_nop 0
	v_writelane_b32 v254, s9, 3
	s_cbranch_vccnz .LBB0_447
	s_waitcnt vmcnt(6)
	v_mbcnt_lo_u32_b32 v0, -1, s1
	v_mbcnt_hi_u32_b32 v0, -1, v0
	s_waitcnt lgkmcnt(0)
	s_add_u32 s1, s6, 0x9600000
	v_add_u32_e32 v64, s72, v0
	s_addc_u32 s2, s7, 0
	s_add_u32 s9, s6, 0xc100000
	v_add_u32_e32 v93, 0xe00, v64
	s_addc_u32 s7, s7, 0
	s_waitcnt vmcnt(4)
	v_and_b32_e32 v9, -8, v93
	s_add_i32 s6, 0, 0x9000
	v_lshlrev_b32_e32 v10, 3, v93
	v_lshlrev_b32_e32 v1, 3, v64
	v_add_u32_e32 v69, 0x200, v64
	v_add_u32_e32 v73, 0x400, v64
	v_add_u32_e32 v77, 0x600, v64
	v_add_u32_e32 v81, 0x800, v64
	v_add_u32_e32 v85, 0xa00, v64
	v_add_u32_e32 v89, 0xc00, v64
	v_add3_u32 v98, s6, v9, v10
	s_lshl_b32 s6, s64, 9
	v_add_u32_e32 v65, 0, v1
	v_and_b32_e32 v2, -8, v64
	v_and_b32_e32 v3, -8, v69
	v_and_b32_e32 v4, -8, v73
	v_and_b32_e32 v5, -8, v77
	v_and_b32_e32 v6, -8, v81
	v_and_b32_e32 v7, -8, v85
	v_and_b32_e32 v8, -8, v89
	s_add_i32 s6, s6, 0
	v_add_u32_e32 v66, v65, v2
	v_add_u32_e32 v70, v65, v3
	v_add_u32_e32 v74, v65, v4
	v_add_u32_e32 v78, v65, v5
	v_add_u32_e32 v82, v65, v6
	v_add_u32_e32 v86, v65, v7
	v_add_u32_e32 v90, v65, v8
	v_add_u32_e32 v94, v65, v9
	s_add_i32 s17, 0, 0x12000
	v_lshlrev_b32_e32 v11, 3, v69
	v_lshlrev_b32_e32 v12, 3, v73
	v_lshlrev_b32_e32 v13, 3, v77
	v_lshlrev_b32_e32 v14, 3, v81
	v_lshlrev_b32_e32 v15, 3, v85
	s_waitcnt vmcnt(2)
	v_lshlrev_b32_e32 v16, 3, v89
	s_add_i32 s18, 0, 0x1b000
	v_lshl_add_u32 v0, v0, 3, s6
	v_add_u32_e32 v67, 0x12000, v66
	v_add_u32_e32 v68, 0x1b000, v66
	v_add_u32_e32 v71, 0x13000, v70
	v_add_u32_e32 v72, 0x1c000, v70
	v_add_u32_e32 v75, 0x14000, v74
	v_add_u32_e32 v76, 0x1d000, v74
	v_add_u32_e32 v79, 0x15000, v78
	v_add_u32_e32 v80, 0x1e000, v78
	v_add_u32_e32 v83, 0x16000, v82
	v_add_u32_e32 v84, 0x1f000, v82
	s_movk_i32 s13, 0xa00
	v_add_u32_e32 v87, 0x17000, v86
	v_add_u32_e32 v88, 0x20000, v86
	s_movk_i32 s16, 0xc00
	v_add_u32_e32 v91, 0x18000, v90
	v_add_u32_e32 v92, 0x21000, v90
	v_add_u32_e32 v95, 0x7000, v94
	v_add_u32_e32 v96, 0x19000, v94
	v_add_u32_e32 v97, 0x22000, v94
	v_add3_u32 v99, s17, v1, v2
	v_add3_u32 v100, s17, v3, v11
	v_add3_u32 v101, s17, v4, v12
	v_add3_u32 v102, s17, v5, v13
	v_add3_u32 v103, s17, v6, v14
	v_add3_u32 v104, s17, v7, v15
	v_add3_u32 v105, s17, v8, v16
	v_add3_u32 v106, s17, v9, v10
	v_add3_u32 v107, s18, v1, v2
	v_add3_u32 v108, s18, v3, v11
	v_add3_u32 v109, s18, v4, v12
	v_add3_u32 v110, s18, v5, v13
	v_add3_u32 v111, s18, v6, v14
	v_add3_u32 v112, s18, v7, v15
	v_add3_u32 v113, s18, v8, v16
	v_add3_u32 v114, s18, v9, v10
	v_sub_u32_e32 v115, 0, v64
	v_add_u32_e32 v116, 0xa000, v0
	s_mov_b32 s6, 0x3f3504f3
	s_mov_b32 s8, 0xbf3504f3
	s_brev_b32 s12, 60
	s_mov_b32 s19, s93

.LBB0_513:
	s_waitcnt lgkmcnt(0)
	v_readfirstlane_b32 s1, v2
	v_readfirstlane_b32 s10, v0
	s_lshl_b32 s0, s0, 8
	s_add_u32 s8, s6, s0
	s_addc_u32 s9, s7, 0
	v_mov_b32_e32 v3, 0x1000
	v_mov_b32_e32 v4, 1
	v_mov_b32_e32 v0, 0x2000
	global_atomic_add v3, v3, v4, s[8:9] offset:1024 sc0
	s_mul_i32 s1, s1, 4
	s_mul_i32 s10, s10, 4
	s_mov_b32 s13, 0
	s_waitcnt vmcnt(0)
	v_readfirstlane_b32 s11, v3
	s_add_u32 s11, s11, 1
	s_cmp_lg_u32 s11, s1
	s_cbranch_scc1 .Lxb3_wait
	buffer_wbl2 sc1
	buffer_inv sc1
	s_waitcnt vmcnt(0)
	v_mov_b32_e32 v3, 0x3000
	global_atomic_add v3, v3, v4, s[6:7] offset:1024 sc0
	s_waitcnt vmcnt(0)
	v_readfirstlane_b32 s11, v3
	s_add_u32 s11, s11, 1
	s_cmp_lg_u32 s11, s10
	s_cbranch_scc1 .Lxb3_poll
	v_mov_b32_e32 v5, 0x3000
	global_atomic_add v0, v4, s[6:7] offset:1024
	global_atomic_add v0, v4, s[6:7] offset:1280
	global_atomic_add v0, v4, s[6:7] offset:1536
	global_atomic_add v0, v4, s[6:7] offset:1792
	global_atomic_add v0, v4, s[6:7] offset:2048
	global_atomic_add v0, v4, s[6:7] offset:2304
	global_atomic_add v0, v4, s[6:7] offset:2560
	global_atomic_add v0, v4, s[6:7] offset:2816
	global_atomic_add v0, v4, s[6:7] offset:3072
	global_atomic_add v0, v4, s[6:7] offset:3328
	global_atomic_add v0, v4, s[6:7] offset:3584
	global_atomic_add v0, v4, s[6:7] offset:3840
	global_atomic_add v5, v4, s[6:7]
	global_atomic_add v5, v4, s[6:7] offset:256
	global_atomic_add v5, v4, s[6:7] offset:512
	global_atomic_add v5, v4, s[6:7] offset:768
	s_waitcnt vmcnt(0)
	s_branch .Lxb3_done

.Lxb3_poll:
	global_load_dword v1, v0, s[8:9] offset:1024 sc1
	s_add_u32 s13, s13, 1
	s_waitcnt vmcnt(0)
	v_readfirstlane_b32 s12, v1
	s_cmp_lg_u32 s12, 3
	s_cbranch_scc1 .Lxb3_rel
	s_cmp_lt_u32 s13, 0x40000
	s_cbranch_scc0 .Lxb3_rel
	s_sleep 1
	s_branch .Lxb3_poll
.Lxb3_rel:
.Lxb3_done:
.LBB0_549:
	s_or_b64 exec, exec, s[4:5]
	s_waitcnt lgkmcnt(0)
	s_barrier
	s_load_dwordx2 s[8:9], s[82:83], 0xb0
	s_load_dwordx2 s[10:11], s[82:83], 0x0
	s_load_dwordx2 s[12:13], s[82:83], 0x10
	v_readlane_b32 s4, v254, 2
	v_readlane_b32 s5, v254, 3
	s_mov_b32 s1, 0
	s_and_b64 vcc, exec, s[4:5]
	s_cbranch_vccz .LBB0_552
	s_mov_b64 s[14:15], 0
	s_cmpk_gt_u32 s93, 0x15f
	s_mov_b64 s[6:7], 0
	s_cbranch_scc1 .LBB0_553
	s_and_b32 s0, s93, 0xff
	s_mulk_i32 s0, 0xab
	s_lshr_b32 s2, s0, 10
	s_mul_i32 s2, s2, 6
	s_sub_i32 s2, s93, s2
	s_lshr_b32 s4, s0, 12
	s_and_b32 s2, s2, 0xff
	s_or_b32 s4, s4, 64
	s_and_b32 s28, s4, 0x4f
	s_bfe_u32 s68, s0, 0x2000a
	s_lshl_b32 s4, s2, 8
	s_mov_b32 s0, 4
	s_mov_b64 s[6:7], -1
	s_branch .LBB0_553

.LBB0_630:
	s_waitcnt lgkmcnt(0)
	v_readfirstlane_b32 s1, v2
	v_readfirstlane_b32 s10, v0
	s_lshl_b32 s0, s0, 8
	s_add_u32 s8, s6, s0
	s_addc_u32 s9, s7, 0
	v_mov_b32_e32 v3, 0x1000
	v_mov_b32_e32 v4, 1
	v_mov_b32_e32 v0, 0x2000
	global_atomic_add v3, v3, v4, s[8:9] offset:1024 sc0
	s_mul_i32 s1, s1, 5
	s_mul_i32 s10, s10, 5
	s_mov_b32 s13, 0
	s_waitcnt vmcnt(0)
	v_readfirstlane_b32 s11, v3
	s_add_u32 s11, s11, 1
	s_cmp_lg_u32 s11, s1
	s_cbranch_scc1 .Lxb4_wait
	buffer_wbl2 sc1
	buffer_inv sc1
	s_waitcnt vmcnt(0)
	v_mov_b32_e32 v3, 0x3000
	global_atomic_add v3, v3, v4, s[6:7] offset:1024 sc0
	s_waitcnt vmcnt(0)
	v_readfirstlane_b32 s11, v3
	s_add_u32 s11, s11, 1
	s_cmp_lg_u32 s11, s10
	s_cbranch_scc1 .Lxb4_poll
	v_mov_b32_e32 v5, 0x3000
	global_atomic_add v0, v4, s[6:7] offset:1024
	global_atomic_add v0, v4, s[6:7] offset:1280
	global_atomic_add v0, v4, s[6:7] offset:1536
	global_atomic_add v0, v4, s[6:7] offset:1792
	global_atomic_add v0, v4, s[6:7] offset:2048
	global_atomic_add v0, v4, s[6:7] offset:2304
	global_atomic_add v0, v4, s[6:7] offset:2560
	global_atomic_add v0, v4, s[6:7] offset:2816
	global_atomic_add v0, v4, s[6:7] offset:3072
	global_atomic_add v0, v4, s[6:7] offset:3328
	global_atomic_add v0, v4, s[6:7] offset:3584
	global_atomic_add v0, v4, s[6:7] offset:3840
	global_atomic_add v5, v4, s[6:7]
	global_atomic_add v5, v4, s[6:7] offset:256
	global_atomic_add v5, v4, s[6:7] offset:512
	global_atomic_add v5, v4, s[6:7] offset:768
	s_waitcnt vmcnt(0)
	s_branch .Lxb4_done

.Lxb4_poll:
	global_load_dword v1, v0, s[8:9] offset:1024 sc1
	s_add_u32 s13, s13, 1
	s_waitcnt vmcnt(0)
	v_readfirstlane_b32 s12, v1
	s_cmp_lg_u32 s12, 4
	s_cbranch_scc1 .Lxb4_rel
	s_cmp_lt_u32 s13, 0x40000
	s_cbranch_scc0 .Lxb4_rel
	s_sleep 1
	s_branch .Lxb4_poll
.Lxb4_rel:
.Lxb4_done:
.LBB0_666:
	s_or_b64 exec, exec, s[4:5]
	s_mov_b32 s1, 0
	s_waitcnt lgkmcnt(0)
	s_barrier
	s_load_dwordx2 s[4:5], s[82:83], 0xb0
	s_load_dwordx2 s[10:11], s[82:83], 0x10
	s_cmpk_lt_i32 s90, 0x400
	s_cselect_b64 s[8:9], -1, 0
	s_cmpk_gt_i32 s90, 0x3ff
	s_mov_b32 s0, 0
	s_cbranch_scc1 .LBB0_671
	v_mbcnt_lo_u32_b32 v0, -1, s1
	v_mbcnt_hi_u32_b32 v0, -1, v0
	v_lshlrev_b32_e32 v4, 2, v0
	v_ashrrev_i32_e32 v5, 31, v4
	v_lshlrev_b64 v[8:9], 2, v[4:5]
	s_waitcnt lgkmcnt(0)
	v_lshl_add_u64 v[2:3], s[4:5], 0, v[8:9]
	s_mov_b64 s[12:13], 0x2a000
	v_cmp_eq_u32_e64 s[6:7], 0, v0
	v_lshl_add_u64 v[0:1], v[2:3], 0, s[12:13]
	s_mov_b64 s[12:13], 0x64000
	s_ashr_i32 s91, s90, 31
	v_lshl_add_u64 v[2:3], v[2:3], 0, s[12:13]
	s_lshl_b64 s[12:13], s[90:91], 2
	s_add_u32 s1, s12, 0x80000
	s_addc_u32 s2, s13, 0
	s_lshl_b64 s[14:15], s[90:91], 11
	v_xor_b32_e32 v24, 0x80, v4
	s_ashr_i32 s89, s88, 31
	v_lshl_add_u64 v[4:5], v[4:5], 1, s[14:15]
	s_mov_b64 s[14:15], 0x9400000
	s_lshl_b64 s[16:17], s[90:91], 12
	s_lshl_b64 s[12:13], s[88:89], 2
	v_lshl_add_u64 v[6:7], v[4:5], 0, s[14:15]
	s_lshl_b64 s[14:15], s[88:89], 11
	v_lshl_add_u64 v[8:9], s[16:17], 0, v[8:9]
	s_lshl_b64 s[16:17], s[88:89], 12
	s_mov_b32 s20, 0x5000000
	v_mov_b32_e32 v25, 0
	s_mov_b32 s21, s90
	s_branch .LBB0_669

.LBB0_689:
	s_waitcnt lgkmcnt(0)
	v_readfirstlane_b32 s1, v2
	v_readfirstlane_b32 s12, v0
	s_lshl_b32 s0, s0, 8
	s_add_u32 s10, s6, s0
	s_addc_u32 s11, s7, 0
	v_mov_b32_e32 v3, 0x1000
	v_mov_b32_e32 v4, 1
	v_mov_b32_e32 v0, 0x2000
	global_atomic_add v3, v3, v4, s[10:11] offset:1024 sc0
	s_mul_i32 s1, s1, 6
	s_mul_i32 s12, s12, 6
	s_mov_b32 s15, 0
	s_waitcnt vmcnt(0)
	v_readfirstlane_b32 s13, v3
	s_add_u32 s13, s13, 1
	s_cmp_lg_u32 s13, s1
	s_cbranch_scc1 .Lxb5_wait
	buffer_wbl2 sc1
	buffer_inv sc1
	s_waitcnt vmcnt(0)
	v_mov_b32_e32 v3, 0x3000
	global_atomic_add v3, v3, v4, s[6:7] offset:1024 sc0
	s_waitcnt vmcnt(0)
	v_readfirstlane_b32 s13, v3
	s_add_u32 s13, s13, 1
	s_cmp_lg_u32 s13, s12
	s_cbranch_scc1 .Lxb5_poll
	v_mov_b32_e32 v5, 0x3000
	global_atomic_add v0, v4, s[6:7] offset:1024
	global_atomic_add v0, v4, s[6:7] offset:1280
	global_atomic_add v0, v4, s[6:7] offset:1536
	global_atomic_add v0, v4, s[6:7] offset:1792
	global_atomic_add v0, v4, s[6:7] offset:2048
	global_atomic_add v0, v4, s[6:7] offset:2304
	global_atomic_add v0, v4, s[6:7] offset:2560
	global_atomic_add v0, v4, s[6:7] offset:2816
	global_atomic_add v0, v4, s[6:7] offset:3072
	global_atomic_add v0, v4, s[6:7] offset:3328
	global_atomic_add v0, v4, s[6:7] offset:3584
	global_atomic_add v0, v4, s[6:7] offset:3840
	global_atomic_add v5, v4, s[6:7]
	global_atomic_add v5, v4, s[6:7] offset:256
	global_atomic_add v5, v4, s[6:7] offset:512
	global_atomic_add v5, v4, s[6:7] offset:768
	s_waitcnt vmcnt(0)
	s_branch .Lxb5_done

.Lxb5_poll:
	global_load_dword v1, v0, s[10:11] offset:1024 sc1
	s_add_u32 s15, s15, 1
	s_waitcnt vmcnt(0)
	v_readfirstlane_b32 s14, v1
	s_cmp_lg_u32 s14, 5
	s_cbranch_scc1 .Lxb5_rel
	s_cmp_lt_u32 s15, 0x40000
	s_cbranch_scc0 .Lxb5_rel
	s_sleep 1
	s_branch .Lxb5_poll
.Lxb5_rel:
.Lxb5_done:
.LBB0_725:
	s_or_b64 exec, exec, s[4:5]
	s_waitcnt lgkmcnt(0)
	s_barrier
	s_load_dwordx2 s[6:7], s[82:83], 0xb0
	s_mov_b32 s36, 0
	s_mov_b32 s0, 0
	s_cmpk_gt_i32 s93, 0x5d7
	s_cbranch_scc1 .LBB0_741
	v_mbcnt_lo_u32_b32 v0, -1, s0
	v_mbcnt_hi_u32_b32 v10, -1, v0
	v_lshl_add_u32 v0, v10, 4, s3
	v_add_u32_e32 v1, 0x2000, v0
	v_ashrrev_i32_e32 v2, 31, v1
	v_lshrrev_b32_e32 v2, 22, v2
	v_add_u32_e32 v2, v1, v2
	v_ashrrev_i32_e32 v8, 10, v2
	v_mul_i32_i24_e32 v2, 0x400, v8
	v_sub_u32_e32 v1, v1, v2
	v_lshrrev_b32_e32 v2, 4, v1
	v_bitop3_b32 v1, v2, v1, 32 bitop3:0x6c
	v_ashrrev_i32_e32 v2, 31, v1
	v_lshrrev_b32_e32 v2, 26, v2
	v_add_u32_e32 v2, v1, v2
	v_ashrrev_i32_e32 v9, 6, v2
	v_lshlrev_b32_e32 v3, 3, v8
	v_and_b32_e32 v2, 0xffc0, v2
	v_and_b32_e32 v3, -16, v3
	v_sub_u32_e32 v1, v1, v2
	v_add_u32_e32 v3, v9, v3
	v_lshrrev_b16_e32 v2, 7, v1
	v_and_b32_e32 v4, 3, v9
	s_mov_b32 s0, 0x1fffe0
	v_lshrrev_b32_e32 v5, 2, v3
	v_lshlrev_b32_e32 v6, 1, v3
	v_and_b32_e32 v2, 1, v2
	v_and_or_b32 v4, v3, s0, v4
	v_and_b32_e32 v5, 4, v5
	v_and_b32_e32 v6, 24, v6
	v_add_u16_e32 v1, v1, v2
	v_mov_b32_e32 v2, 1
	v_or3_b32 v4, v4, v5, v6
	v_lshlrev_b32_e32 v5, 5, v8
	v_ashrrev_i16_sdwa v1, v2, sext(v1) dst_sel:DWORD dst_unused:UNUSED_PAD src0_sel:DWORD src1_sel:BYTE_0
	v_and_b32_e32 v5, 32, v5
	v_bfe_i32 v11, v1, 0, 16
	v_add_lshl_u32 v1, v5, v11, 1
	v_lshl_add_u32 v136, v4, 11, v1
	v_lshl_add_u32 v138, v3, 11, v1
	v_ashrrev_i32_e32 v1, 31, v0
	v_lshrrev_b32_e32 v1, 22, v1
	v_add_u32_e32 v1, v0, v1
	v_ashrrev_i32_e32 v12, 10, v1
	v_mul_i32_i24_e32 v1, 0x400, v12
	v_sub_u32_e32 v0, v0, v1
	v_lshrrev_b32_e32 v1, 4, v0
	v_bitop3_b32 v0, v1, v0, 32 bitop3:0x6c
	v_ashrrev_i32_e32 v1, 31, v0
	v_lshrrev_b32_e32 v1, 26, v1
	s_waitcnt lgkmcnt(0)
	s_add_u32 s37, s6, 0x7400000
	v_add_u32_e32 v1, v0, v1
	v_lshlrev_b32_e32 v3, 3, v12
	s_addc_u32 s38, s7, 0
	v_ashrrev_i32_e32 v13, 6, v1
	v_and_b32_e32 v3, -16, v3
	s_add_u32 s39, s6, 0x680000
	v_add_u32_e32 v3, v13, v3
	v_and_b32_e32 v4, 3, v13
	s_addc_u32 s40, s7, 0
	v_and_or_b32 v4, v3, s0, v4
	s_ashr_i32 s0, s93, 31
	s_lshr_b32 s0, s0, 29
	s_add_i32 s0, s93, s0
	s_ashr_i32 s1, s0, 3
	s_and_b32 s0, s0, -8
	s_sub_i32 s0, s93, s0
	s_cmp_lt_i32 s0, 0
	s_movk_i32 s41, 0xbc
	s_cselect_b32 s2, s41, 0xbb
	s_mul_i32 s0, s0, s2
	s_add_i32 s0, s0, s1
	s_mul_hi_i32 s1, s0, 0x2e8ba2e9
	s_lshr_b32 s2, s1, 31
	s_ashr_i32 s1, s1, 4
	s_add_i32 s1, s1, s2
	s_lshl_b32 s2, s1, 2
	s_mulk_i32 s1, 0x58
	s_sub_i32 s0, s0, s1
	s_bfe_i32 s1, s0, 0x80000
	s_bfe_u32 s1, s1, 0x2000d
	s_add_i32 s1, s0, s1
	s_bfe_i32 s4, s1, 0x80000
	s_and_b32 s1, s1, 0xfc
	s_sub_i32 s0, s0, s1
	s_sext_i32_i16 s4, s4
	s_sext_i32_i8 s0, s0
	v_lshrrev_b32_e32 v5, 2, v3
	v_lshlrev_b32_e32 v6, 1, v3
	v_and_b32_e32 v1, 0xc0, v1
	s_lshr_b32 s18, s4, 2
	s_add_i32 s4, s2, s0
	v_and_b32_e32 v5, 4, v5
	v_and_b32_e32 v6, 24, v6
	v_sub_u32_e32 v0, v0, v1
	s_ashr_i32 s5, s4, 31
	s_bfe_i64 s[10:11], s[18:19], 0x100000
	v_or3_b32 v4, v4, v5, v6
	v_lshlrev_b32_e32 v5, 5, v12
	v_ashrrev_i16_sdwa v0, v2, sext(v0) dst_sel:DWORD dst_unused:UNUSED_PAD src0_sel:DWORD src1_sel:BYTE_0
	s_lshl_b64 s[0:1], s[4:5], 19
	s_lshl_b64 s[10:11], s[10:11], 19
	v_and_b32_e32 v5, 32, v5
	v_bfe_i32 v14, v0, 0, 16
	s_add_u32 s30, s39, s10
	v_add_lshl_u32 v0, v5, v14, 1
	s_addc_u32 s31, s40, s11
	s_add_i32 s42, s3, 0
	v_lshl_add_u32 v140, v4, 11, v0
	s_add_i32 m0, s42, 0x10000
	v_lshl_add_u32 v142, v3, 11, v0
	global_load_lds_dwordx4 v140, s[30:31]
	s_add_i32 m0, s42, 0x12000
	s_add_u32 s10, s30, 0x40000
	global_load_lds_dwordx4 v136, s[30:31]
	s_addc_u32 s11, s31, 0
	s_add_i32 m0, s42, 0x14000
	v_mov_b32_e32 v141, 0
	global_load_lds_dwordx4 v140, s[10:11]
	s_add_i32 m0, s42, 0x16000
	s_add_u32 s28, s37, s0
	s_addc_u32 s29, s38, s1
	s_add_i32 s43, s42, 0x2000
	global_load_lds_dwordx4 v136, s[10:11]
	s_mov_b32 m0, s42
	s_add_u32 s0, s28, 0x40000
	global_load_lds_dwordx4 v142, s[28:29]
	s_mov_b32 m0, s43
	s_addc_u32 s1, s29, 0
	s_add_i32 s44, s42, 0x4000
	global_load_lds_dwordx4 v138, s[28:29]
	s_mov_b32 m0, s44
	s_add_i32 s45, s42, 0x6000
	global_load_lds_dwordx4 v142, s[0:1]
	s_mov_b32 m0, s45
	v_mov_b32_e32 v137, v141
	global_load_lds_dwordx4 v138, s[0:1]
	v_mov_b32_e32 v143, v141
	v_mov_b32_e32 v139, v141
	s_cmp_eq_u32 s84, 1
	v_lshl_add_u64 v[6:7], s[30:31], 0, v[140:141]
	v_lshl_add_u64 v[4:5], s[30:31], 0, v[136:137]
	v_lshl_add_u64 v[0:1], s[28:29], 0, v[142:143]
	s_cselect_b64 s[10:11], -1, 0
	s_cmp_lg_u32 s84, 1
	v_lshl_add_u64 v[2:3], s[28:29], 0, v[138:139]
	s_cbranch_scc1 .LBB0_728
	s_barrier

.LBB0_759:
	s_waitcnt lgkmcnt(0)
	v_readfirstlane_b32 s1, v2
	v_readfirstlane_b32 s12, v0
	s_lshl_b32 s0, s0, 8
	s_add_u32 s10, s6, s0
	s_addc_u32 s11, s7, 0
	v_mov_b32_e32 v3, 0x1000
	v_mov_b32_e32 v4, 1
	v_mov_b32_e32 v0, 0x2000
	global_atomic_add v3, v3, v4, s[10:11] offset:1024 sc0
	s_mul_i32 s1, s1, 7
	s_mul_i32 s12, s12, 7
	s_mov_b32 s15, 0
	s_waitcnt vmcnt(0)
	v_readfirstlane_b32 s13, v3
	s_add_u32 s13, s13, 1
	s_cmp_lg_u32 s13, s1
	s_cbranch_scc1 .Lxb6_wait
	buffer_wbl2 sc1
	buffer_inv sc1
	s_waitcnt vmcnt(0)
	v_mov_b32_e32 v3, 0x3000
	global_atomic_add v3, v3, v4, s[6:7] offset:1024 sc0
	s_waitcnt vmcnt(0)
	v_readfirstlane_b32 s13, v3
	s_add_u32 s13, s13, 1
	s_cmp_lg_u32 s13, s12
	s_cbranch_scc1 .Lxb6_poll
	v_mov_b32_e32 v5, 0x3000
	global_atomic_add v0, v4, s[6:7] offset:1024
	global_atomic_add v0, v4, s[6:7] offset:1280
	global_atomic_add v0, v4, s[6:7] offset:1536
	global_atomic_add v0, v4, s[6:7] offset:1792
	global_atomic_add v0, v4, s[6:7] offset:2048
	global_atomic_add v0, v4, s[6:7] offset:2304
	global_atomic_add v0, v4, s[6:7] offset:2560
	global_atomic_add v0, v4, s[6:7] offset:2816
	global_atomic_add v0, v4, s[6:7] offset:3072
	global_atomic_add v0, v4, s[6:7] offset:3328
	global_atomic_add v0, v4, s[6:7] offset:3584
	global_atomic_add v0, v4, s[6:7] offset:3840
	global_atomic_add v5, v4, s[6:7]
	global_atomic_add v5, v4, s[6:7] offset:256
	global_atomic_add v5, v4, s[6:7] offset:512
	global_atomic_add v5, v4, s[6:7] offset:768
	s_waitcnt vmcnt(0)
	s_branch .Lxb6_done

.Lxb6_poll:
	global_load_dword v1, v0, s[10:11] offset:1024 sc1
	s_add_u32 s15, s15, 1
	s_waitcnt vmcnt(0)
	v_readfirstlane_b32 s14, v1
	s_cmp_lg_u32 s14, 6
	s_cbranch_scc1 .Lxb6_rel
	s_cmp_lt_u32 s15, 0x40000
	s_cbranch_scc0 .Lxb6_rel
	s_sleep 1
	s_branch .Lxb6_poll
.Lxb6_rel:
.Lxb6_done:
.LBB0_795:
	s_or_b64 exec, exec, s[4:5]
	s_waitcnt lgkmcnt(0)
	s_barrier
	s_load_dwordx2 s[10:11], s[82:83], 0xb0
	s_load_dwordx2 s[12:13], s[82:83], 0xa8
	v_readlane_b32 s4, v254, 2
	v_readlane_b32 s5, v254, 3
	s_mov_b32 s1, 0
	s_and_b64 vcc, exec, s[4:5]
	s_cbranch_vccz .LBB0_798
	s_mov_b64 s[14:15], 0
	s_cmpk_gt_u32 s93, 0x1af
	s_mov_b64 s[6:7], 0
	s_cbranch_scc1 .LBB0_799
	s_and_b32 s0, s93, 0xff
	s_mul_i32 s2, s0, 0x75
	s_lshr_b32 s2, s2, 8
	s_sub_i32 s4, s93, s2
	s_bfe_u32 s4, s4, 0x70001
	s_add_i32 s4, s4, s2
	s_bfe_u32 s2, s4, 0x50003
	s_mul_i32 s2, s2, 11
	s_mulk_i32 s0, 0xbb
	s_sub_i32 s2, s93, s2
	s_lshr_b32 s0, s0, 13
	s_and_b32 s2, s2, 0xff
	s_or_b32 s0, s0, 64
	s_and_b32 s28, s0, 0x47
	s_bfe_u32 s66, s4, 0x20003
	s_lshl_b32 s4, s2, 8
	s_mov_b32 s0, 4
	s_mov_b64 s[6:7], -1
	s_branch .LBB0_799

.LBB0_870:
	s_waitcnt lgkmcnt(0)
	v_readfirstlane_b32 s1, v2
	v_readfirstlane_b32 s12, v0
	s_lshl_b32 s0, s0, 8
	s_add_u32 s10, s6, s0
	s_addc_u32 s11, s7, 0
	v_mov_b32_e32 v3, 0x1000
	v_mov_b32_e32 v4, 1
	v_mov_b32_e32 v0, 0x2000
	global_atomic_add v3, v3, v4, s[10:11] offset:1024 sc0
	s_mul_i32 s1, s1, 8
	s_mul_i32 s12, s12, 8
	s_mov_b32 s15, 0
	s_waitcnt vmcnt(0)
	v_readfirstlane_b32 s13, v3
	s_add_u32 s13, s13, 1
	s_cmp_lg_u32 s13, s1
	s_cbranch_scc1 .Lxb7_wait
	buffer_wbl2 sc1
	buffer_inv sc1
	s_waitcnt vmcnt(0)
	v_mov_b32_e32 v3, 0x3000
	global_atomic_add v3, v3, v4, s[6:7] offset:1024 sc0
	s_waitcnt vmcnt(0)
	v_readfirstlane_b32 s13, v3
	s_add_u32 s13, s13, 1
	s_cmp_lg_u32 s13, s12
	s_cbranch_scc1 .Lxb7_poll
	v_mov_b32_e32 v5, 0x3000
	global_atomic_add v0, v4, s[6:7] offset:1024
	global_atomic_add v0, v4, s[6:7] offset:1280
	global_atomic_add v0, v4, s[6:7] offset:1536
	global_atomic_add v0, v4, s[6:7] offset:1792
	global_atomic_add v0, v4, s[6:7] offset:2048
	global_atomic_add v0, v4, s[6:7] offset:2304
	global_atomic_add v0, v4, s[6:7] offset:2560
	global_atomic_add v0, v4, s[6:7] offset:2816
	global_atomic_add v0, v4, s[6:7] offset:3072
	global_atomic_add v0, v4, s[6:7] offset:3328
	global_atomic_add v0, v4, s[6:7] offset:3584
	global_atomic_add v0, v4, s[6:7] offset:3840
	global_atomic_add v5, v4, s[6:7]
	global_atomic_add v5, v4, s[6:7] offset:256
	global_atomic_add v5, v4, s[6:7] offset:512
	global_atomic_add v5, v4, s[6:7] offset:768
	s_waitcnt vmcnt(0)
	s_branch .Lxb7_done

.Lxb7_poll:
	global_load_dword v1, v0, s[10:11] offset:1024 sc1
	s_add_u32 s15, s15, 1
	s_waitcnt vmcnt(0)
	v_readfirstlane_b32 s14, v1
	s_cmp_lg_u32 s14, 7
	s_cbranch_scc1 .Lxb7_rel
	s_cmp_lt_u32 s15, 0x40000
	s_cbranch_scc0 .Lxb7_rel
	s_sleep 1
	s_branch .Lxb7_poll
.Lxb7_rel:
.Lxb7_done:
.LBB0_906:
	s_or_b64 exec, exec, s[4:5]
	s_mov_b32 s1, 0
	s_waitcnt lgkmcnt(0)
	s_barrier
	s_load_dwordx2 s[4:5], s[82:83], 0xb0
	s_load_dwordx2 s[12:13], s[82:83], 0xa8
	s_andn2_b64 vcc, exec, s[8:9]
	s_mov_b32 s0, 0
	s_cbranch_vccnz .LBB0_911
	v_mbcnt_lo_u32_b32 v0, -1, s1
	v_mbcnt_hi_u32_b32 v0, -1, v0
	v_lshlrev_b32_e32 v4, 2, v0
	v_ashrrev_i32_e32 v5, 31, v4
	v_lshlrev_b64 v[6:7], 2, v[4:5]
	s_waitcnt lgkmcnt(0)
	v_lshl_add_u64 v[2:3], s[4:5], 0, v[6:7]
	s_mov_b64 s[8:9], 0x2d000
	v_cmp_eq_u32_e64 s[6:7], 0, v0
	v_lshl_add_u64 v[0:1], v[2:3], 0, s[8:9]
	s_mov_b64 s[8:9], 0x69000
	s_ashr_i32 s91, s90, 31
	v_lshl_add_u64 v[2:3], v[2:3], 0, s[8:9]
	s_lshl_b64 s[8:9], s[90:91], 2
	s_add_u32 s1, s8, 0x91000
	s_addc_u32 s2, s9, 0
	s_ashr_i32 s89, s88, 31
	s_lshl_b64 s[10:11], s[90:91], 11
	v_xor_b32_e32 v40, 0x80, v4
	s_lshl_b64 s[8:9], s[88:89], 2
	v_lshl_add_u64 v[4:5], v[4:5], 1, s[10:11]
	s_lshl_b64 s[10:11], s[88:89], 11
	s_lshl_b64 s[14:15], s[90:91], 12
	s_add_u32 s12, s12, s14
	s_addc_u32 s13, s13, s15
	v_lshl_add_u64 v[6:7], s[12:13], 0, v[6:7]
	s_lshl_b64 s[12:13], s[88:89], 12
	s_mov_b32 s16, 0x5000000
	s_mov_b32 s17, 0x9400000
	v_mov_b32_e32 v41, 0
	s_mov_b32 s18, s90
	s_branch .LBB0_909

.LBB0_940:
	s_waitcnt lgkmcnt(0)
	v_readfirstlane_b32 s1, v2
	v_readfirstlane_b32 s10, v0
	s_lshl_b32 s0, s0, 8
	s_add_u32 s8, s6, s0
	s_addc_u32 s9, s7, 0
	v_mov_b32_e32 v3, 0x1000
	v_mov_b32_e32 v4, 1
	v_mov_b32_e32 v0, 0x2000
	global_atomic_add v3, v3, v4, s[8:9] offset:1024 sc0
	s_mul_i32 s1, s1, 9
	s_mul_i32 s10, s10, 9
	s_mov_b32 s13, 0
	s_waitcnt vmcnt(0)
	v_readfirstlane_b32 s11, v3
	s_add_u32 s11, s11, 1
	s_cmp_lg_u32 s11, s1
	s_cbranch_scc1 .Lxb8_wait
	buffer_wbl2 sc1
	buffer_inv sc1
	s_waitcnt vmcnt(0)
	v_mov_b32_e32 v3, 0x3000
	global_atomic_add v3, v3, v4, s[6:7] offset:1024 sc0
	s_waitcnt vmcnt(0)
	v_readfirstlane_b32 s11, v3
	s_add_u32 s11, s11, 1
	s_cmp_lg_u32 s11, s10
	s_cbranch_scc1 .Lxb8_poll
	v_mov_b32_e32 v5, 0x3000
	global_atomic_add v0, v4, s[6:7] offset:1024
	global_atomic_add v0, v4, s[6:7] offset:1280
	global_atomic_add v0, v4, s[6:7] offset:1536
	global_atomic_add v0, v4, s[6:7] offset:1792
	global_atomic_add v0, v4, s[6:7] offset:2048
	global_atomic_add v0, v4, s[6:7] offset:2304
	global_atomic_add v0, v4, s[6:7] offset:2560
	global_atomic_add v0, v4, s[6:7] offset:2816
	global_atomic_add v0, v4, s[6:7] offset:3072
	global_atomic_add v0, v4, s[6:7] offset:3328
	global_atomic_add v0, v4, s[6:7] offset:3584
	global_atomic_add v0, v4, s[6:7] offset:3840
	global_atomic_add v5, v4, s[6:7]
	global_atomic_add v5, v4, s[6:7] offset:256
	global_atomic_add v5, v4, s[6:7] offset:512
	global_atomic_add v5, v4, s[6:7] offset:768
	s_waitcnt vmcnt(0)
	s_branch .Lxb8_done

.Lxb8_poll:
	global_load_dword v1, v0, s[8:9] offset:1024 sc1
	s_add_u32 s13, s13, 1
	s_waitcnt vmcnt(0)
	v_readfirstlane_b32 s12, v1
	s_cmp_lg_u32 s12, 8
	s_cbranch_scc1 .Lxb8_rel
	s_cmp_lt_u32 s13, 0x40000
	s_cbranch_scc0 .Lxb8_rel
	s_sleep 1
	s_branch .Lxb8_poll
.Lxb8_rel:
.Lxb8_done:
.LBB0_976:
	s_or_b64 exec, exec, s[4:5]
	s_waitcnt lgkmcnt(0)
	s_barrier
	s_load_dwordx2 s[8:9], s[82:83], 0xb0
	s_mov_b32 s36, 0
	s_mov_b32 s0, 0
	s_cmpk_gt_i32 s93, 0x32f
	s_cbranch_scc1 .LBB0_992
	v_mbcnt_lo_u32_b32 v0, -1, s0
	v_mbcnt_hi_u32_b32 v10, -1, v0
	v_lshl_add_u32 v0, v10, 4, s3
	v_add_u32_e32 v1, 0x2000, v0
	v_ashrrev_i32_e32 v2, 31, v1
	v_lshrrev_b32_e32 v2, 22, v2
	v_add_u32_e32 v2, v1, v2
	v_ashrrev_i32_e32 v8, 10, v2
	v_mul_i32_i24_e32 v2, 0x400, v8
	v_sub_u32_e32 v1, v1, v2
	v_lshrrev_b32_e32 v2, 4, v1
	v_bitop3_b32 v1, v2, v1, 32 bitop3:0x6c
	v_ashrrev_i32_e32 v2, 31, v1
	v_lshrrev_b32_e32 v2, 26, v2
	v_add_u32_e32 v2, v1, v2
	v_ashrrev_i32_e32 v9, 6, v2
	v_lshlrev_b32_e32 v3, 3, v8
	v_and_b32_e32 v2, 0xffc0, v2
	v_and_b32_e32 v3, -16, v3
	v_sub_u32_e32 v1, v1, v2
	v_add_u32_e32 v3, v9, v3
	v_lshrrev_b16_e32 v2, 7, v1
	v_and_b32_e32 v4, 3, v9
	s_mov_b32 s0, 0x1fffe0
	v_lshrrev_b32_e32 v5, 2, v3
	v_lshlrev_b32_e32 v6, 1, v3
	v_and_b32_e32 v2, 1, v2
	v_and_or_b32 v4, v3, s0, v4
	v_and_b32_e32 v5, 4, v5
	v_and_b32_e32 v6, 24, v6
	v_add_u16_e32 v1, v1, v2
	v_mov_b32_e32 v2, 1
	v_or3_b32 v4, v4, v5, v6
	v_lshlrev_b32_e32 v5, 5, v8
	v_ashrrev_i16_sdwa v1, v2, sext(v1) dst_sel:DWORD dst_unused:UNUSED_PAD src0_sel:DWORD src1_sel:BYTE_0
	v_and_b32_e32 v5, 32, v5
	v_bfe_i32 v11, v1, 0, 16
	v_add_lshl_u32 v1, v5, v11, 1
	v_lshl_add_u32 v144, v4, 11, v1
	v_lshl_add_u32 v146, v3, 11, v1
	v_ashrrev_i32_e32 v1, 31, v0
	v_lshrrev_b32_e32 v1, 22, v1
	v_add_u32_e32 v1, v0, v1
	v_ashrrev_i32_e32 v12, 10, v1
	v_mul_i32_i24_e32 v1, 0x400, v12
	v_sub_u32_e32 v0, v0, v1
	v_lshrrev_b32_e32 v1, 4, v0
	v_bitop3_b32 v0, v1, v0, 32 bitop3:0x6c
	v_ashrrev_i32_e32 v1, 31, v0
	v_lshrrev_b32_e32 v1, 26, v1
	s_waitcnt lgkmcnt(0)
	s_add_u32 s37, s8, 0x7400000
	v_add_u32_e32 v1, v0, v1
	v_lshlrev_b32_e32 v3, 3, v12
	s_addc_u32 s38, s9, 0
	v_ashrrev_i32_e32 v13, 6, v1
	v_and_b32_e32 v3, -16, v3
	s_add_u32 s39, s8, 0x1700000
	v_add_u32_e32 v3, v13, v3
	v_and_b32_e32 v4, 3, v13
	s_addc_u32 s40, s9, 0
	v_and_or_b32 v4, v3, s0, v4
	s_ashr_i32 s0, s93, 31
	s_lshr_b32 s0, s0, 29
	s_add_i32 s0, s93, s0
	s_ashr_i32 s1, s0, 3
	s_and_b32 s0, s0, -8
	s_sub_i32 s0, s93, s0
	s_cmp_lt_i32 s0, 0
	s_movk_i32 s41, 0x67
	s_cselect_b32 s2, s41, 0x66
	s_mul_i32 s0, s0, s2
	s_add_i32 s0, s0, s1
	s_mul_hi_i32 s1, s0, 0x2aaaaaab
	s_lshr_b32 s2, s1, 31
	s_ashr_i32 s1, s1, 3
	s_add_i32 s1, s1, s2
	s_lshl_b32 s2, s1, 2
	s_mul_i32 s1, s1, 48
	s_sub_i32 s0, s0, s1
	s_bfe_i32 s1, s0, 0x80000
	s_bfe_u32 s1, s1, 0x2000d
	s_add_i32 s1, s0, s1
	s_bfe_i32 s4, s1, 0x80000
	s_and_b32 s1, s1, 0xfc
	s_sub_i32 s0, s0, s1
	s_sext_i32_i16 s4, s4
	s_sext_i32_i8 s0, s0
	v_lshrrev_b32_e32 v5, 2, v3
	v_lshlrev_b32_e32 v6, 1, v3
	v_and_b32_e32 v1, 0xc0, v1
	s_lshr_b32 s4, s4, 2
	s_add_i32 s26, s2, s0
	v_and_b32_e32 v5, 4, v5
	v_and_b32_e32 v6, 24, v6
	v_sub_u32_e32 v0, v0, v1
	s_ashr_i32 s27, s26, 31
	s_bfe_i64 s[6:7], s[4:5], 0x100000
	v_or3_b32 v4, v4, v5, v6
	v_lshlrev_b32_e32 v5, 5, v12
	v_ashrrev_i16_sdwa v0, v2, sext(v0) dst_sel:DWORD dst_unused:UNUSED_PAD src0_sel:DWORD src1_sel:BYTE_0
	s_lshl_b64 s[0:1], s[26:27], 19
	s_lshl_b64 s[6:7], s[6:7], 19
	v_and_b32_e32 v5, 32, v5
	v_bfe_i32 v14, v0, 0, 16
	s_add_u32 s30, s39, s6
	v_add_lshl_u32 v0, v5, v14, 1
	s_addc_u32 s31, s40, s7
	s_add_i32 s27, s3, 0
	v_lshl_add_u32 v148, v4, 11, v0
	s_add_i32 m0, s27, 0x10000
	v_lshl_add_u32 v150, v3, 11, v0
	global_load_lds_dwordx4 v148, s[30:31]
	s_add_i32 m0, s27, 0x12000
	s_add_u32 s6, s30, 0x40000
	global_load_lds_dwordx4 v144, s[30:31]
	s_addc_u32 s7, s31, 0
	s_add_i32 m0, s27, 0x14000
	v_mov_b32_e32 v149, 0
	global_load_lds_dwordx4 v148, s[6:7]
	s_add_i32 m0, s27, 0x16000
	s_add_u32 s28, s37, s0
	s_addc_u32 s29, s38, s1
	s_add_i32 s42, s27, 0x2000
	global_load_lds_dwordx4 v144, s[6:7]
	s_mov_b32 m0, s27
	s_add_u32 s0, s28, 0x40000
	global_load_lds_dwordx4 v150, s[28:29]
	s_mov_b32 m0, s42
	s_addc_u32 s1, s29, 0
	s_add_i32 s43, s27, 0x4000
	global_load_lds_dwordx4 v146, s[28:29]
	s_mov_b32 m0, s43
	s_add_i32 s44, s27, 0x6000
	global_load_lds_dwordx4 v150, s[0:1]
	s_mov_b32 m0, s44
	v_mov_b32_e32 v145, v149
	global_load_lds_dwordx4 v146, s[0:1]
	v_mov_b32_e32 v151, v149
	v_mov_b32_e32 v147, v149
	s_cmp_eq_u32 s84, 1
	s_mov_b32 s45, 0
	v_lshl_add_u64 v[6:7], s[30:31], 0, v[148:149]
	v_lshl_add_u64 v[4:5], s[30:31], 0, v[144:145]
	v_lshl_add_u64 v[0:1], s[28:29], 0, v[150:151]
	s_cselect_b64 s[10:11], -1, 0
	s_cmp_lg_u32 s84, 1
	v_lshl_add_u64 v[2:3], s[28:29], 0, v[146:147]
	s_cbranch_scc1 .LBB0_979
	s_barrier

.LBB0_1044:
	s_waitcnt lgkmcnt(0)
	v_readfirstlane_b32 s1, v2
	v_readfirstlane_b32 s10, v0
	s_lshl_b32 s0, s0, 8
	s_add_u32 s8, s6, s0
	s_addc_u32 s9, s7, 0
	v_mov_b32_e32 v3, 0x1000
	v_mov_b32_e32 v4, 1
	v_mov_b32_e32 v0, 0x2000
	global_atomic_add v3, v3, v4, s[8:9] offset:1024 sc0
	s_mul_i32 s1, s1, 10
	s_mul_i32 s10, s10, 10
	s_mov_b32 s13, 0
	s_waitcnt vmcnt(0)
	v_readfirstlane_b32 s11, v3
	s_add_u32 s11, s11, 1
	s_cmp_lg_u32 s11, s1
	s_cbranch_scc1 .Lxb9_wait
	buffer_wbl2 sc1
	buffer_inv sc1
	s_waitcnt vmcnt(0)
	v_mov_b32_e32 v3, 0x3000
	global_atomic_add v3, v3, v4, s[6:7] offset:1024 sc0
	s_waitcnt vmcnt(0)
	v_readfirstlane_b32 s11, v3
	s_add_u32 s11, s11, 1
	s_cmp_lg_u32 s11, s10
	s_cbranch_scc1 .Lxb9_poll
	v_mov_b32_e32 v5, 0x3000
	global_atomic_add v0, v4, s[6:7] offset:1024
	global_atomic_add v0, v4, s[6:7] offset:1280
	global_atomic_add v0, v4, s[6:7] offset:1536
	global_atomic_add v0, v4, s[6:7] offset:1792
	global_atomic_add v0, v4, s[6:7] offset:2048
	global_atomic_add v0, v4, s[6:7] offset:2304
	global_atomic_add v0, v4, s[6:7] offset:2560
	global_atomic_add v0, v4, s[6:7] offset:2816
	global_atomic_add v0, v4, s[6:7] offset:3072
	global_atomic_add v0, v4, s[6:7] offset:3328
	global_atomic_add v0, v4, s[6:7] offset:3584
	global_atomic_add v0, v4, s[6:7] offset:3840
	global_atomic_add v5, v4, s[6:7]
	global_atomic_add v5, v4, s[6:7] offset:256
	global_atomic_add v5, v4, s[6:7] offset:512
	global_atomic_add v5, v4, s[6:7] offset:768
	s_waitcnt vmcnt(0)
	s_branch .Lxb9_done

.Lxb9_poll:
	global_load_dword v1, v0, s[8:9] offset:1024 sc1
	s_add_u32 s13, s13, 1
	s_waitcnt vmcnt(0)
	v_readfirstlane_b32 s12, v1
	s_cmp_lg_u32 s12, 9
	s_cbranch_scc1 .Lxb9_rel
	s_cmp_lt_u32 s13, 0x40000
	s_cbranch_scc0 .Lxb9_rel
	s_sleep 1
	s_branch .Lxb9_poll
.Lxb9_rel:
.Lxb9_done:
.LBB0_1080:
	s_or_b64 exec, exec, s[4:5]
	s_mov_b32 s1, 0
	s_waitcnt lgkmcnt(0)
	s_barrier
	s_load_dwordx2 s[4:5], s[82:83], 0xb0
	s_load_dwordx2 s[18:19], s[82:83], 0xa8
	v_readlane_b32 s6, v254, 22
	v_readlane_b32 s7, v254, 23
	s_andn2_b64 vcc, exec, s[6:7]
	s_cbranch_vccz .LBB0_1082
	s_cmpk_gt_i32 s90, 0xfff
	s_cbranch_scc0 .LBB0_1083
	s_branch .LBB0_1110

.LBB0_1128:
	s_waitcnt lgkmcnt(0)
	v_readfirstlane_b32 s1, v2
	v_readfirstlane_b32 s10, v0
	s_lshl_b32 s0, s0, 8
	s_add_u32 s8, s6, s0
	s_addc_u32 s9, s7, 0
	v_mov_b32_e32 v3, 0x1000
	v_mov_b32_e32 v4, 1
	v_mov_b32_e32 v0, 0x2000
	global_atomic_add v3, v3, v4, s[8:9] offset:1024 sc0
	s_mul_i32 s1, s1, 11
	s_mul_i32 s10, s10, 11
	s_mov_b32 s13, 0
	s_waitcnt vmcnt(0)
	v_readfirstlane_b32 s11, v3
	s_add_u32 s11, s11, 1
	s_cmp_lg_u32 s11, s1
	s_cbranch_scc1 .Lxb10_wait
	buffer_wbl2 sc1
	buffer_inv sc1
	s_waitcnt vmcnt(0)
	v_mov_b32_e32 v3, 0x3000
	global_atomic_add v3, v3, v4, s[6:7] offset:1024 sc0
	s_waitcnt vmcnt(0)
	v_readfirstlane_b32 s11, v3
	s_add_u32 s11, s11, 1
	s_cmp_lg_u32 s11, s10
	s_cbranch_scc1 .Lxb10_poll
	v_mov_b32_e32 v5, 0x3000
	global_atomic_add v0, v4, s[6:7] offset:1024
	global_atomic_add v0, v4, s[6:7] offset:1280
	global_atomic_add v0, v4, s[6:7] offset:1536
	global_atomic_add v0, v4, s[6:7] offset:1792
	global_atomic_add v0, v4, s[6:7] offset:2048
	global_atomic_add v0, v4, s[6:7] offset:2304
	global_atomic_add v0, v4, s[6:7] offset:2560
	global_atomic_add v0, v4, s[6:7] offset:2816
	global_atomic_add v0, v4, s[6:7] offset:3072
	global_atomic_add v0, v4, s[6:7] offset:3328
	global_atomic_add v0, v4, s[6:7] offset:3584
	global_atomic_add v0, v4, s[6:7] offset:3840
	global_atomic_add v5, v4, s[6:7]
	global_atomic_add v5, v4, s[6:7] offset:256
	global_atomic_add v5, v4, s[6:7] offset:512
	global_atomic_add v5, v4, s[6:7] offset:768
	s_waitcnt vmcnt(0)
	s_branch .Lxb10_done

.Lxb10_poll:
	global_load_dword v1, v0, s[8:9] offset:1024 sc1
	s_add_u32 s13, s13, 1
	s_waitcnt vmcnt(0)
	v_readfirstlane_b32 s12, v1
	s_cmp_lg_u32 s12, 10
	s_cbranch_scc1 .Lxb10_rel
	s_cmp_lt_u32 s13, 0x40000
	s_cbranch_scc0 .Lxb10_rel
	s_sleep 1
	s_branch .Lxb10_poll
.Lxb10_rel:
.Lxb10_done:
.LBB0_1164:
	s_or_b64 exec, exec, s[4:5]
	s_waitcnt lgkmcnt(0)
	s_barrier
	s_load_dwordx2 s[6:7], s[82:83], 0xb0
	s_load_dwordx2 s[8:9], s[82:83], 0xa8
	s_mov_b32 s0, 0
	s_and_b64 vcc, exec, s[58:59]
	s_cbranch_vccnz .LBB0_1170
	s_ashr_i32 s1, s93, 31
	s_lshr_b32 s1, s1, 29
	s_add_i32 s1, s93, s1
	s_and_b32 s2, s1, -8
	s_sub_i32 s2, s93, s2
	s_cmp_gt_i32 s2, -1
	s_cbranch_scc0 .LBB0_1167
	s_lshl_b32 s10, s2, 5
	s_cbranch_execz .LBB0_1168
	s_branch .LBB0_1169

.LBB0_1224:
	s_waitcnt lgkmcnt(0)
	v_readfirstlane_b32 s1, v2
	v_readfirstlane_b32 s10, v0
	s_lshl_b32 s0, s0, 8
	s_add_u32 s8, s6, s0
	s_addc_u32 s9, s7, 0
	v_mov_b32_e32 v3, 0x1000
	v_mov_b32_e32 v4, 1
	v_mov_b32_e32 v0, 0x2000
	global_atomic_add v3, v3, v4, s[8:9] offset:1024 sc0
	s_mul_i32 s1, s1, 12
	s_mul_i32 s10, s10, 12
	s_mov_b32 s13, 0
	s_waitcnt vmcnt(0)
	v_readfirstlane_b32 s11, v3
	s_add_u32 s11, s11, 1
	s_cmp_lg_u32 s11, s1
	s_cbranch_scc1 .Lxb11_wait
	buffer_wbl2 sc1
	buffer_inv sc1
	s_waitcnt vmcnt(0)
	v_mov_b32_e32 v3, 0x3000
	global_atomic_add v3, v3, v4, s[6:7] offset:1024 sc0
	s_waitcnt vmcnt(0)
	v_readfirstlane_b32 s11, v3
	s_add_u32 s11, s11, 1
	s_cmp_lg_u32 s11, s10
	s_cbranch_scc1 .Lxb11_poll
	v_mov_b32_e32 v5, 0x3000
	global_atomic_add v0, v4, s[6:7] offset:1024
	global_atomic_add v0, v4, s[6:7] offset:1280
	global_atomic_add v0, v4, s[6:7] offset:1536
	global_atomic_add v0, v4, s[6:7] offset:1792
	global_atomic_add v0, v4, s[6:7] offset:2048
	global_atomic_add v0, v4, s[6:7] offset:2304
	global_atomic_add v0, v4, s[6:7] offset:2560
	global_atomic_add v0, v4, s[6:7] offset:2816
	global_atomic_add v0, v4, s[6:7] offset:3072
	global_atomic_add v0, v4, s[6:7] offset:3328
	global_atomic_add v0, v4, s[6:7] offset:3584
	global_atomic_add v0, v4, s[6:7] offset:3840
	global_atomic_add v5, v4, s[6:7]
	global_atomic_add v5, v4, s[6:7] offset:256
	global_atomic_add v5, v4, s[6:7] offset:512
	global_atomic_add v5, v4, s[6:7] offset:768
	s_waitcnt vmcnt(0)
	s_branch .Lxb11_done

.Lxb11_poll:
	global_load_dword v1, v0, s[8:9] offset:1024 sc1
	s_add_u32 s13, s13, 1
	s_waitcnt vmcnt(0)
	v_readfirstlane_b32 s12, v1
	s_cmp_lg_u32 s12, 11
	s_cbranch_scc1 .Lxb11_rel
	s_cmp_lt_u32 s13, 0x40000
	s_cbranch_scc0 .Lxb11_rel
	s_sleep 1
	s_branch .Lxb11_poll
.Lxb11_rel:
.Lxb11_done:
.LBB0_1260:
	s_or_b64 exec, exec, s[4:5]
	s_waitcnt lgkmcnt(0)
	s_barrier
	s_load_dwordx2 s[6:7], s[82:83], 0xb0
	s_load_dwordx2 s[8:9], s[82:83], 0xa8
	s_mov_b32 s36, 0
	s_mov_b32 s0, 0
	s_cmpk_gt_i32 s93, 0x57f
	s_cbranch_scc1 .LBB0_1276
	v_mbcnt_lo_u32_b32 v0, -1, s0
	v_mbcnt_hi_u32_b32 v10, -1, v0
	v_lshl_add_u32 v0, v10, 4, s3
	v_add_u32_e32 v1, 0x2000, v0
	v_ashrrev_i32_e32 v2, 31, v1
	v_lshrrev_b32_e32 v2, 22, v2
	v_add_u32_e32 v2, v1, v2
	v_ashrrev_i32_e32 v8, 10, v2
	v_mul_i32_i24_e32 v2, 0x400, v8
	v_sub_u32_e32 v1, v1, v2
	v_lshrrev_b32_e32 v2, 4, v1
	v_bitop3_b32 v1, v2, v1, 32 bitop3:0x6c
	v_ashrrev_i32_e32 v2, 31, v1
	v_lshrrev_b32_e32 v2, 26, v2
	v_add_u32_e32 v2, v1, v2
	v_ashrrev_i32_e32 v9, 6, v2
	v_lshlrev_b32_e32 v3, 3, v8
	v_and_b32_e32 v2, 0xffc0, v2
	v_and_b32_e32 v3, -16, v3
	v_sub_u32_e32 v1, v1, v2
	v_add_u32_e32 v3, v9, v3
	v_lshrrev_b16_e32 v2, 7, v1
	v_and_b32_e32 v4, 3, v9
	s_mov_b32 s0, 0x1fffe0
	v_lshrrev_b32_e32 v5, 2, v3
	v_lshlrev_b32_e32 v6, 1, v3
	v_and_b32_e32 v2, 1, v2
	v_and_or_b32 v4, v3, s0, v4
	v_and_b32_e32 v5, 4, v5
	v_and_b32_e32 v6, 24, v6
	v_add_u16_e32 v1, v1, v2
	v_mov_b32_e32 v2, 1
	v_or3_b32 v4, v4, v5, v6
	v_lshlrev_b32_e32 v5, 5, v8
	v_ashrrev_i16_sdwa v1, v2, sext(v1) dst_sel:DWORD dst_unused:UNUSED_PAD src0_sel:DWORD src1_sel:BYTE_0
	v_and_b32_e32 v5, 32, v5
	v_bfe_i32 v11, v1, 0, 16
	v_add_lshl_u32 v1, v5, v11, 1
	s_waitcnt vmcnt(11)
	v_lshl_add_u32 v136, v4, 11, v1
	v_lshl_add_u32 v138, v3, 11, v1
	v_ashrrev_i32_e32 v1, 31, v0
	v_lshrrev_b32_e32 v1, 22, v1
	v_add_u32_e32 v1, v0, v1
	v_ashrrev_i32_e32 v12, 10, v1
	v_mul_i32_i24_e32 v1, 0x400, v12
	v_sub_u32_e32 v0, v0, v1
	v_lshrrev_b32_e32 v1, 4, v0
	v_bitop3_b32 v0, v1, v0, 32 bitop3:0x6c
	v_ashrrev_i32_e32 v1, 31, v0
	v_lshrrev_b32_e32 v1, 26, v1
	v_add_u32_e32 v1, v0, v1
	v_lshlrev_b32_e32 v3, 3, v12
	v_ashrrev_i32_e32 v13, 6, v1
	v_and_b32_e32 v3, -16, v3
	s_waitcnt lgkmcnt(0)
	s_add_u32 s37, s6, 0x1f00000
	v_add_u32_e32 v3, v13, v3
	v_and_b32_e32 v4, 3, v13
	s_addc_u32 s38, s7, 0
	v_and_or_b32 v4, v3, s0, v4
	s_ashr_i32 s0, s93, 31
	s_lshr_b32 s0, s0, 29
	s_add_i32 s0, s93, s0
	s_ashr_i32 s1, s0, 3
	s_and_b32 s0, s0, -8
	s_sub_i32 s0, s93, s0
	s_cmp_lt_i32 s0, 0
	s_movk_i32 s39, 0xb1
	s_cselect_b32 s2, s39, 0xb0
	s_mul_i32 s0, s0, s2
	s_add_i32 s0, s0, s1
	s_mul_hi_i32 s1, s0, 0x2e8ba2e9
	s_lshr_b32 s2, s1, 31
	s_ashr_i32 s1, s1, 4
	s_add_i32 s1, s1, s2
	s_lshl_b32 s2, s1, 2
	s_mulk_i32 s1, 0x58
	s_sub_i32 s0, s0, s1
	s_bfe_i32 s1, s0, 0x80000
	s_bfe_u32 s1, s1, 0x2000d
	s_add_i32 s1, s0, s1
	s_bfe_i32 s4, s1, 0x80000
	s_and_b32 s1, s1, 0xfc
	s_sub_i32 s0, s0, s1
	s_sext_i32_i16 s4, s4
	s_sext_i32_i8 s0, s0
	v_lshrrev_b32_e32 v5, 2, v3
	v_lshlrev_b32_e32 v6, 1, v3
	v_and_b32_e32 v1, 0xc0, v1
	s_lshr_b32 s18, s4, 2
	s_add_i32 s4, s2, s0
	v_and_b32_e32 v5, 4, v5
	v_and_b32_e32 v6, 24, v6
	v_sub_u32_e32 v0, v0, v1
	s_ashr_i32 s5, s4, 31
	s_bfe_i64 s[10:11], s[18:19], 0x100000
	v_or3_b32 v4, v4, v5, v6
	v_lshlrev_b32_e32 v5, 5, v12
	v_ashrrev_i16_sdwa v0, v2, sext(v0) dst_sel:DWORD dst_unused:UNUSED_PAD src0_sel:DWORD src1_sel:BYTE_0
	s_lshl_b64 s[0:1], s[4:5], 19
	s_lshl_b64 s[10:11], s[10:11], 19
	v_and_b32_e32 v5, 32, v5
	v_bfe_i32 v14, v0, 0, 16
	s_add_u32 s30, s37, s10
	v_add_lshl_u32 v0, v5, v14, 1
	s_addc_u32 s31, s38, s11
	s_add_i32 s40, s3, 0
	s_waitcnt vmcnt(9)
	v_lshl_add_u32 v140, v4, 11, v0
	s_add_i32 m0, s40, 0x10000
	v_lshl_add_u32 v142, v3, 11, v0
	global_load_lds_dwordx4 v140, s[30:31]
	s_add_i32 m0, s40, 0x12000
	s_add_u32 s10, s30, 0x40000
	global_load_lds_dwordx4 v136, s[30:31]
	s_addc_u32 s11, s31, 0
	s_add_i32 m0, s40, 0x14000
	v_mov_b32_e32 v141, 0
	global_load_lds_dwordx4 v140, s[10:11]
	s_add_i32 m0, s40, 0x16000
	s_add_u32 s28, s8, s0
	s_addc_u32 s29, s9, s1
	s_add_i32 s41, s40, 0x2000
	global_load_lds_dwordx4 v136, s[10:11]
	s_mov_b32 m0, s40
	s_add_u32 s0, s28, 0x40000
	global_load_lds_dwordx4 v142, s[28:29]
	s_mov_b32 m0, s41
	s_addc_u32 s1, s29, 0
	s_add_i32 s42, s40, 0x4000
	global_load_lds_dwordx4 v138, s[28:29]
	s_mov_b32 m0, s42
	s_add_i32 s43, s40, 0x6000
	global_load_lds_dwordx4 v142, s[0:1]
	s_mov_b32 m0, s43
	v_mov_b32_e32 v137, v141
	global_load_lds_dwordx4 v138, s[0:1]
	v_mov_b32_e32 v143, v141
	v_mov_b32_e32 v139, v141
	s_cmp_eq_u32 s84, 1
	v_lshl_add_u64 v[6:7], s[30:31], 0, v[140:141]
	v_lshl_add_u64 v[4:5], s[30:31], 0, v[136:137]
	v_lshl_add_u64 v[0:1], s[28:29], 0, v[142:143]
	s_cselect_b64 s[10:11], -1, 0
	s_cmp_lg_u32 s84, 1
	v_lshl_add_u64 v[2:3], s[28:29], 0, v[138:139]
	s_cbranch_scc1 .LBB0_1263
	s_barrier

.LBB0_1294:
	s_waitcnt lgkmcnt(0)
	v_readfirstlane_b32 s1, v2
	v_readfirstlane_b32 s10, v0
	s_lshl_b32 s0, s0, 8
	s_add_u32 s8, s6, s0
	s_addc_u32 s9, s7, 0
	v_mov_b32_e32 v3, 0x1000
	v_mov_b32_e32 v4, 1
	v_mov_b32_e32 v0, 0x2000
	global_atomic_add v3, v3, v4, s[8:9] offset:1024 sc0
	s_mul_i32 s1, s1, 13
	s_mul_i32 s10, s10, 13
	s_mov_b32 s13, 0
	s_waitcnt vmcnt(0)
	v_readfirstlane_b32 s11, v3
	s_add_u32 s11, s11, 1
	s_cmp_lg_u32 s11, s1
	s_cbranch_scc1 .Lxb12_wait
	buffer_wbl2 sc1
	buffer_inv sc1
	s_waitcnt vmcnt(0)
	v_mov_b32_e32 v3, 0x3000
	global_atomic_add v3, v3, v4, s[6:7] offset:1024 sc0
	s_waitcnt vmcnt(0)
	v_readfirstlane_b32 s11, v3
	s_add_u32 s11, s11, 1
	s_cmp_lg_u32 s11, s10
	s_cbranch_scc1 .Lxb12_poll
	v_mov_b32_e32 v5, 0x3000
	global_atomic_add v0, v4, s[6:7] offset:1024
	global_atomic_add v0, v4, s[6:7] offset:1280
	global_atomic_add v0, v4, s[6:7] offset:1536
	global_atomic_add v0, v4, s[6:7] offset:1792
	global_atomic_add v0, v4, s[6:7] offset:2048
	global_atomic_add v0, v4, s[6:7] offset:2304
	global_atomic_add v0, v4, s[6:7] offset:2560
	global_atomic_add v0, v4, s[6:7] offset:2816
	global_atomic_add v0, v4, s[6:7] offset:3072
	global_atomic_add v0, v4, s[6:7] offset:3328
	global_atomic_add v0, v4, s[6:7] offset:3584
	global_atomic_add v0, v4, s[6:7] offset:3840
	global_atomic_add v5, v4, s[6:7]
	global_atomic_add v5, v4, s[6:7] offset:256
	global_atomic_add v5, v4, s[6:7] offset:512
	global_atomic_add v5, v4, s[6:7] offset:768
	s_waitcnt vmcnt(0)
	s_branch .Lxb12_done

.Lxb12_poll:
	global_load_dword v1, v0, s[8:9] offset:1024 sc1
	s_add_u32 s13, s13, 1
	s_waitcnt vmcnt(0)
	v_readfirstlane_b32 s12, v1
	s_cmp_lg_u32 s12, 12
	s_cbranch_scc1 .Lxb12_rel
	s_cmp_lt_u32 s13, 0x40000
	s_cbranch_scc0 .Lxb12_rel
	s_sleep 1
	s_branch .Lxb12_poll
.Lxb12_rel:
.Lxb12_done:
.LBB0_1330:
	s_or_b64 exec, exec, s[4:5]
	s_waitcnt lgkmcnt(0)
	s_barrier
	s_load_dwordx2 s[4:5], s[82:83], 0xb0
	s_load_dwordx2 s[6:7], s[82:83], 0xa8
	s_mov_b32 s8, 0
	s_and_b64 vcc, exec, s[58:59]
	s_cbranch_vccnz .LBB0_1358
	s_ashr_i32 s0, s93, 31
	s_lshr_b32 s0, s0, 29
	s_add_i32 s10, s93, s0
	s_and_b32 s0, s10, -8
	s_sub_i32 s9, s93, s0
	s_cmp_gt_i32 s9, -1
	s_cbranch_scc0 .LBB0_1333
	s_lshl_b32 s2, s9, 5
	s_ashr_i32 s1, s10, 3
	s_cbranch_execz .LBB0_1334
	s_branch .LBB0_1335
